# speedup vs baseline: 1.0135x; 1.0067x over previous
; DEV int tid_opaque() { int t = threadIdx.x; asm volatile("" : "+v"(t)); return t; }
; DEV void cache_convert(const Params& p, int l, int vb, int vnb, float* sm) {
;     const int gt = vb * 256 + tid_opaque(), gn = vnb * 256;
;     for (int i = gt; i < 8 * PAST * 96; i += gn) {
; __global__ void __launch_bounds__(256, 2) fwd_kernel(Params p) {
;     ...
;         if (ph == 0 || (ph == 8 && bid >= 64)) cache_convert(pq, ph == 0 ? 0 : 1, ph == 0 ? bid : bid - 64, ph == 0 ? nb : nb - 64, (float*)smem);
.LBB0_2706:
	v_readlane_b32 s0, v254, 6
	v_readlane_b32 s1, v254, 7
	s_andn2_b64 vcc, exec, s[0:1]
	s_mov_b64 s[0:1], s[94:95]
	s_cbranch_vccnz .LBB0_2708
	s_cmp_eq_u32 s82, 4
	s_cselect_b64 s[0:1], -1, 0
	s_cmp_gt_i32 s78, 15
	s_cselect_b64 s[2:3], -1, 0
	s_and_b64 s[0:1], s[0:1], s[2:3]
.LBB0_2708:
	s_andn2_b64 vcc, exec, s[0:1]
	v_readlane_b32 s4, v254, 4
	v_readlane_b32 s5, v254, 5
	s_cbranch_vccnz .LBB0_2750
	s_sub_i32 s2, s78, 16
	s_and_b64 s[0:1], s[94:95], exec
	s_cselect_b32 s6, s78, s2
	s_sub_i32 s2, s4, 16
	v_mov_b32_e32 v0, v186
	s_and_b64 s[0:1], s[94:95], exec
	s_cselect_b32 s7, s4, s2
	s_and_b64 s[0:1], s[94:95], exec
	s_cbranch_scc0 .Lcc_skip
	s_addk_i32 s7, 0xff40
	s_cmp_ge_i32 s6, s7
	s_cselect_b32 s6, 0x10000, s6
